# sparse attention: V^T tile re-laid out (keys a lane needs for one PV MFMA contiguous, xor-swizzled rows of 128 B) so each V^T fragment is one ds_read_b128 instead of two ds_read_b64; the loaded piece
# baseline (speedup 1.0000x reference)
.LBB0_2063:
	s_or_b64 exec, exec, s[0:1]
	s_cmpk_gt_i32 s90, 0x3ff
	v_readlane_b32 s68, v251, 50
	v_readlane_b32 s69, v251, 51
	s_waitcnt lgkmcnt(0)
	s_barrier
	s_cbranch_scc1 .LBB0_2167
	v_readlane_b32 s0, v251, 7
	v_and_b32_e32 v112, 15, v152
	v_lshrrev_b32_e32 v113, 4, v152
	s_nop 1
	s_and_b32 s34, s0, 3
	s_lshr_b32 s35, s0, 2
	v_lshrrev_b32_e32 v220, 3, v153
	v_and_b32_e32 v221, 7, v153
	v_and_b32_e32 v222, 7, v220
	v_xor_b32_e32 v222, v222, v221
	v_lshlrev_b32_e32 v222, 4, v222
	v_lshl_add_u32 v114, v220, 7, v222
	v_and_b32_e32 v222, 4, v221
	v_and_b32_e32 v223, 1, v221
	v_lshl_or_b32 v222, v223, 1, v222
	v_and_b32_e32 v223, 7, v220
	v_xor_b32_e32 v222, v222, v223
	v_lshlrev_b32_e32 v222, 4, v222
	v_lshl_add_u32 v123, v220, 7, v222
	v_bfe_u32 v223, v221, 1, 1
	v_lshl_add_u32 v123, v223, 3, v123
	v_add_u32_e32 v123, 0x2000, v123
	v_mul_u32_u24_e32 v117, 0x600, v220
	v_lshl_add_u32 v117, v221, 4, v117
	v_lshlrev_b32_e32 v118, 12, v220
	v_lshl_add_u32 v118, v221, 4, v118
	v_and_b32_e32 v222, 7, v112
	v_xor_b32_e32 v222, v222, v113
	v_lshlrev_b32_e32 v222, 4, v222
	v_lshl_add_u32 v116, v112, 7, v222
	v_add_u32_e32 v116, 0x2000, v116
	v_and_b32_e32 v222, 7, v112
	v_xor_b32_e32 v222, v222, v113
	v_lshlrev_b32_e32 v222, 4, v222
	v_lshl_add_u32 v115, v112, 7, v222
	v_xor_b32_e32 v122, 64, v115
	s_lshl_b32 s1, s0, 13
	s_add_i32 s1, s1, 0x9000
	v_lshl_add_u32 v250, v152, 4, s1
	v_mov_b32_e32 v226, 0xf149f2ca
	v_mov_b32_e32 v227, 0xff61b1e6
	v_mov_b32_e32 v203, 0x41000000
	v_mov_b32_e32 v238, 0
	v_mov_b32_e32 v224, 0xff800000
	s_mov_b32 s26, s90
	s_mov_b32 s50, 0

.Lnsa_ready_2_w:
	s_ff1_i32_b32 s15, s38
	s_add_i32 s65, s38, -1
	s_and_b32 s38, s38, s65
	s_ff1_i32_b32 s41, s38
	s_add_i32 s65, s38, -1
	s_and_b32 s38, s38, s65
	s_ff1_i32_b32 s42, s38
	s_add_i32 s65, s38, -1
	s_and_b32 s38, s38, s65
	s_max_i32 s65, s41, 0
	s_mul_i32 s56, s65, 0x18000
	s_lshl_b32 s58, s65, 7
	s_add_u32 s56, s46, s56
	s_addc_u32 s57, s47, 0
	s_add_u32 s58, s48, s58
	s_addc_u32 s59, s49, 0
	global_load_dwordx4 v[96:99], v117, s[56:57]
	global_load_dwordx4 v[100:103], v118, s[58:59]
	s_max_i32 s65, s42, 0
	s_mul_i32 s56, s65, 0x18000
	s_lshl_b32 s58, s65, 7
	s_add_u32 s56, s46, s56
	s_addc_u32 s57, s47, 0
	s_add_u32 s58, s48, s58
	s_addc_u32 s59, s49, 0
	global_load_dwordx4 v[104:107], v117, s[56:57]
	global_load_dwordx4 v[108:111], v118, s[58:59]
	s_waitcnt vmcnt(4)
	v_add_u32_e32 v244, s50, v114
	v_add_u32_e32 v245, s50, v123
	ds_write_b128 v244, v[192:195]
	v_xor_b32_e32 v241, 16, v245
	ds_write_b64 v245, v[196:197]
	ds_write_b64 v241, v[198:199]
	s_branch .Lnsa_ready_2_x
.Lnsa_ready_2:
	s_waitcnt vmcnt(4)
	v_add_u32_e32 v244, s50, v114
	v_add_u32_e32 v245, s50, v123
	ds_write_b128 v244, v[88:91]
	v_xor_b32_e32 v241, 16, v245
	ds_write_b64 v245, v[92:93]
	ds_write_b64 v241, v[94:95]

.Lnsa_loop_3:
	s_cmp_lt_i32 s15, 0
	s_cbranch_scc1 .Lnsa_brk_4
	s_waitcnt lgkmcnt(0)
	v_mfma_f32_16x16x32_bf16 v[64:67], v[16:19], v[212:215], v[64:67]
	s_lshl_b32 s44, s15, 6
	s_lshl_b32 s65, 1, s15
	v_and_b32_e32 v220, s65, v248
	v_mfma_f32_16x16x32_bf16 v[68:71], v[24:27], v[212:215], v[68:71]
	v_and_b32_e32 v221, s65, v249
	v_cmp_ne_u32_e64 s[60:61], 0, v220
	v_cmp_ne_u32_e64 s[62:63], 0, v221
	v_mfma_f32_16x16x32_bf16 v[72:75], v[32:35], v[212:215], v[72:75]
	s_cmp_eq_u32 s15, s32
	s_cselect_b32 s64, 1, 0
	s_cmp_eq_u32 s15, s14
	v_mfma_f32_16x16x32_bf16 v[76:79], v[40:43], v[212:215], v[76:79]
	s_cselect_b32 s64, 1, s64
	s_xor_b32 s17, s50, 0x4800
	v_add_u32_e32 v244, s17, v114
	v_mfma_f32_16x16x32_bf16 v[64:67], v[20:23], v[216:219], v[64:67]
	v_add_u32_e32 v245, s17, v123
	v_add_u32_e32 v247, s50, v116
	v_xor_b32_e32 v241, 16, v245
	v_mfma_f32_16x16x32_bf16 v[68:71], v[28:31], v[216:219], v[68:71]
	v_xor_b32_e32 v246, 64, v247
	v_cndmask_b32_e64 v228, v227, v80, s[60:61]
	v_cndmask_b32_e64 v229, v227, v80, s[60:61]
	v_mfma_f32_16x16x32_bf16 v[72:75], v[36:39], v[216:219], v[72:75]
	v_cndmask_b32_e64 v230, v227, v80, s[60:61]
	v_cndmask_b32_e64 v231, v227, v80, s[60:61]
	v_cndmask_b32_e64 v236, v227, v81, s[62:63]
	v_mfma_f32_16x16x32_bf16 v[76:79], v[44:47], v[216:219], v[76:79]
	v_cndmask_b32_e64 v237, v227, v81, s[62:63]
	v_cndmask_b32_e64 v238, v227, v81, s[62:63]
	v_cndmask_b32_e64 v239, v227, v81, s[62:63]
	ds_read_b128 v[16:19], v247 offset:0
	ds_read_b128 v[20:23], v246 offset:0
	ds_read_b128 v[24:27], v247 offset:2048
	ds_read_b128 v[28:31], v246 offset:2048
	ds_read_b128 v[32:35], v247 offset:4096
	ds_read_b128 v[36:39], v246 offset:4096
	ds_read_b128 v[40:43], v247 offset:6144
	ds_read_b128 v[44:47], v246 offset:6144
	v_mfma_f32_16x16x32_bf16 v[124:127], v[160:163], v[0:3], v[228:231]
	s_waitcnt vmcnt(4)
	ds_write_b128 v244, v[96:99]
	v_mfma_f32_16x16x32_bf16 v[128:131], v[168:171], v[0:3], v[228:231]
	ds_write_b64 v245, v[100:101]
	ds_write_b64 v241, v[102:103]
	v_mfma_f32_16x16x32_bf16 v[132:135], v[176:179], v[0:3], v[228:231]
	s_mov_b32 s16, s41
	s_ff1_i32_b32 s41, s38
	v_mfma_f32_16x16x32_bf16 v[136:139], v[184:187], v[0:3], v[228:231]
	s_add_i32 s65, s38, -1
	s_and_b32 s38, s38, s65
	v_mfma_f32_16x16x32_bf16 v[124:127], v[164:167], v[4:7], v[124:127]
	s_max_i32 s65, s41, 0
	s_mul_i32 s56, s65, 0x18000
	v_mfma_f32_16x16x32_bf16 v[128:131], v[172:175], v[4:7], v[128:131]
	s_lshl_b32 s58, s65, 7
	s_add_u32 s56, s46, s56
	v_mfma_f32_16x16x32_bf16 v[132:135], v[180:183], v[4:7], v[132:135]
	s_addc_u32 s57, s47, 0
	s_add_u32 s58, s48, s58
	v_mfma_f32_16x16x32_bf16 v[136:139], v[188:191], v[4:7], v[136:139]
	s_addc_u32 s59, s49, 0
	global_load_dwordx4 v[96:99], v117, s[56:57]
	global_load_dwordx4 v[100:103], v118, s[58:59]
	s_cmp_eq_u32 s64, 0
	s_cbranch_scc1 .Lnsa_nm_5
	v_lshl_add_u32 v222, v113, 2, s44
	v_sub_u32_e32 v120, v86, v222
	v_cndmask_b32_e64 v240, -1, v120, s[60:61]
	v_subrev_u32_e32 v220, 0, v240
	v_subrev_u32_e32 v221, 1, v240
	v_subrev_u32_e32 v222, 2, v240
	v_subrev_u32_e32 v223, 3, v240
	v_cmp_gt_u32_e64 s[52:53], s45, v220
	v_cmp_gt_u32_e64 s[54:55], s45, v221
	v_cmp_gt_u32_e64 s[56:57], s45, v222
	v_cmp_gt_u32_e64 s[58:59], s45, v223
	v_cndmask_b32_e64 v124, v224, v124, s[52:53]
	v_cndmask_b32_e64 v125, v224, v125, s[54:55]
	v_cndmask_b32_e64 v126, v224, v126, s[56:57]
	v_cndmask_b32_e64 v127, v224, v127, s[58:59]
	v_subrev_u32_e32 v220, 16, v240
	v_subrev_u32_e32 v221, 17, v240
	v_subrev_u32_e32 v222, 18, v240
	v_subrev_u32_e32 v223, 19, v240
	v_cmp_gt_u32_e64 s[52:53], s45, v220
	v_cmp_gt_u32_e64 s[54:55], s45, v221
	v_cmp_gt_u32_e64 s[56:57], s45, v222
	v_cmp_gt_u32_e64 s[58:59], s45, v223
	v_cndmask_b32_e64 v128, v224, v128, s[52:53]
	v_cndmask_b32_e64 v129, v224, v129, s[54:55]
	v_cndmask_b32_e64 v130, v224, v130, s[56:57]
	v_cndmask_b32_e64 v131, v224, v131, s[58:59]
	v_subrev_u32_e32 v220, 32, v240
	v_subrev_u32_e32 v221, 33, v240
	v_subrev_u32_e32 v222, 34, v240
	v_subrev_u32_e32 v223, 35, v240
	v_cmp_gt_u32_e64 s[52:53], s45, v220
	v_cmp_gt_u32_e64 s[54:55], s45, v221
	v_cmp_gt_u32_e64 s[56:57], s45, v222
	v_cmp_gt_u32_e64 s[58:59], s45, v223
	v_cndmask_b32_e64 v132, v224, v132, s[52:53]
	v_cndmask_b32_e64 v133, v224, v133, s[54:55]
	v_cndmask_b32_e64 v134, v224, v134, s[56:57]
	v_cndmask_b32_e64 v135, v224, v135, s[58:59]
	v_subrev_u32_e32 v220, 48, v240
	v_subrev_u32_e32 v221, 49, v240
	v_subrev_u32_e32 v222, 50, v240
	v_subrev_u32_e32 v223, 51, v240
	v_cmp_gt_u32_e64 s[52:53], s45, v220
	v_cmp_gt_u32_e64 s[54:55], s45, v221
	v_cmp_gt_u32_e64 s[56:57], s45, v222
	v_cmp_gt_u32_e64 s[58:59], s45, v223
	v_cndmask_b32_e64 v136, v224, v136, s[52:53]
	v_cndmask_b32_e64 v137, v224, v137, s[54:55]
	v_cndmask_b32_e64 v138, v224, v138, s[56:57]
	v_cndmask_b32_e64 v139, v224, v139, s[58:59]

.Lnsa_rb_9:
	s_waitcnt lgkmcnt(0)
	s_barrier
	s_mov_b32 s50, s17
	s_mov_b32 s15, s16
	v_add_u32_e32 v225, s50, v115
	v_add_u32_e32 v246, s50, v122
	ds_read_b128 v[160:163], v225 offset:0
	ds_read_b128 v[168:171], v225 offset:2048
	ds_read_b128 v[176:179], v225 offset:4096
	ds_read_b128 v[184:187], v225 offset:6144
	ds_read_b128 v[164:167], v246 offset:0
	ds_read_b128 v[172:175], v246 offset:2048
	ds_read_b128 v[180:183], v246 offset:4096
	ds_read_b128 v[188:191], v246 offset:6144
	v_mfma_f32_16x16x32_bf16 v[48:51], v[16:19], v[204:207], v[48:51]
	v_exp_f32_e32 v140, v140
	v_exp_f32_e32 v141, v141
	v_exp_f32_e32 v142, v142
	v_exp_f32_e32 v143, v143
	v_mfma_f32_16x16x32_bf16 v[52:55], v[24:27], v[204:207], v[52:55]
	v_exp_f32_e32 v144, v144
	v_exp_f32_e32 v145, v145
	v_exp_f32_e32 v146, v146
	v_exp_f32_e32 v147, v147
	v_mfma_f32_16x16x32_bf16 v[56:59], v[32:35], v[204:207], v[56:59]
	v_exp_f32_e32 v148, v148
	v_exp_f32_e32 v149, v149
	v_exp_f32_e32 v150, v150
	v_exp_f32_e32 v151, v151
	v_mfma_f32_16x16x32_bf16 v[60:63], v[40:43], v[204:207], v[60:63]
	v_exp_f32_e32 v154, v154
	v_exp_f32_e32 v155, v155
	v_exp_f32_e32 v156, v156
	v_exp_f32_e32 v157, v157
	v_mfma_f32_16x16x32_bf16 v[48:51], v[20:23], v[208:211], v[48:51]
	v_add_f32_e32 v232, v140, v141
	v_add_f32_e32 v232, v232, v142
	v_add_f32_e32 v232, v232, v143
	v_add_f32_e32 v232, v232, v144
	v_mfma_f32_16x16x32_bf16 v[52:55], v[28:31], v[208:211], v[52:55]
	v_add_f32_e32 v232, v232, v145
	v_add_f32_e32 v232, v232, v146
	v_add_f32_e32 v232, v232, v147
	v_add_f32_e32 v232, v232, v148
	v_mfma_f32_16x16x32_bf16 v[56:59], v[36:39], v[208:211], v[56:59]
	v_add_f32_e32 v232, v232, v149
	v_add_f32_e32 v232, v232, v150
	v_add_f32_e32 v232, v232, v151
	v_add_f32_e32 v232, v232, v154
	v_mfma_f32_16x16x32_bf16 v[60:63], v[44:47], v[208:211], v[60:63]
	v_add_f32_e32 v232, v232, v155
	v_add_f32_e32 v232, v232, v156
	v_add_f32_e32 v232, v232, v157
	v_add_f32_e32 v83, v83, v232
	v_cvt_pk_bf16_f32 v212, v140, v141
	v_cvt_pk_bf16_f32 v213, v142, v143
	v_cvt_pk_bf16_f32 v214, v144, v145
	v_cvt_pk_bf16_f32 v215, v146, v147
	v_cvt_pk_bf16_f32 v216, v148, v149
	v_cvt_pk_bf16_f32 v217, v150, v151
	v_cvt_pk_bf16_f32 v218, v154, v155
	v_cvt_pk_bf16_f32 v219, v156, v157
	s_cmp_lt_i32 s15, 0
	s_cbranch_scc1 .Lnsa_brk_4
	s_waitcnt lgkmcnt(0)
	v_mfma_f32_16x16x32_bf16 v[64:67], v[16:19], v[212:215], v[64:67]
	s_lshl_b32 s44, s15, 6
	s_lshl_b32 s65, 1, s15
	v_and_b32_e32 v220, s65, v248
	v_mfma_f32_16x16x32_bf16 v[68:71], v[24:27], v[212:215], v[68:71]
	v_and_b32_e32 v221, s65, v249
	v_cmp_ne_u32_e64 s[60:61], 0, v220
	v_cmp_ne_u32_e64 s[62:63], 0, v221
	v_mfma_f32_16x16x32_bf16 v[72:75], v[32:35], v[212:215], v[72:75]
	s_cmp_eq_u32 s15, s32
	s_cselect_b32 s64, 1, 0
	s_cmp_eq_u32 s15, s14
	v_mfma_f32_16x16x32_bf16 v[76:79], v[40:43], v[212:215], v[76:79]
	s_cselect_b32 s64, 1, s64
	s_xor_b32 s17, s50, 0x4800
	v_add_u32_e32 v244, s17, v114
	v_mfma_f32_16x16x32_bf16 v[64:67], v[20:23], v[216:219], v[64:67]
	v_add_u32_e32 v245, s17, v123
	v_add_u32_e32 v247, s50, v116
	v_xor_b32_e32 v241, 16, v245
	v_mfma_f32_16x16x32_bf16 v[68:71], v[28:31], v[216:219], v[68:71]
	v_xor_b32_e32 v246, 64, v247
	v_cndmask_b32_e64 v228, v227, v80, s[60:61]
	v_cndmask_b32_e64 v229, v227, v80, s[60:61]
	v_mfma_f32_16x16x32_bf16 v[72:75], v[36:39], v[216:219], v[72:75]
	v_cndmask_b32_e64 v230, v227, v80, s[60:61]
	v_cndmask_b32_e64 v231, v227, v80, s[60:61]
	v_cndmask_b32_e64 v236, v227, v81, s[62:63]
	v_mfma_f32_16x16x32_bf16 v[76:79], v[44:47], v[216:219], v[76:79]
	v_cndmask_b32_e64 v237, v227, v81, s[62:63]
	v_cndmask_b32_e64 v238, v227, v81, s[62:63]
	v_cndmask_b32_e64 v239, v227, v81, s[62:63]
	ds_read_b128 v[16:19], v247 offset:0
	ds_read_b128 v[20:23], v246 offset:0
	ds_read_b128 v[24:27], v247 offset:2048
	ds_read_b128 v[28:31], v246 offset:2048
	ds_read_b128 v[32:35], v247 offset:4096
	ds_read_b128 v[36:39], v246 offset:4096
	ds_read_b128 v[40:43], v247 offset:6144
	ds_read_b128 v[44:47], v246 offset:6144
	v_mfma_f32_16x16x32_bf16 v[124:127], v[160:163], v[0:3], v[228:231]
	s_waitcnt vmcnt(4)
	ds_write_b128 v244, v[104:107]
	v_mfma_f32_16x16x32_bf16 v[128:131], v[168:171], v[0:3], v[228:231]
	ds_write_b64 v245, v[108:109]
	ds_write_b64 v241, v[110:111]
	v_mfma_f32_16x16x32_bf16 v[132:135], v[176:179], v[0:3], v[228:231]
	s_mov_b32 s16, s42
	s_ff1_i32_b32 s42, s38
	v_mfma_f32_16x16x32_bf16 v[136:139], v[184:187], v[0:3], v[228:231]
	s_add_i32 s65, s38, -1
	s_and_b32 s38, s38, s65
	v_mfma_f32_16x16x32_bf16 v[124:127], v[164:167], v[4:7], v[124:127]
	s_max_i32 s65, s42, 0
	s_mul_i32 s56, s65, 0x18000
	v_mfma_f32_16x16x32_bf16 v[128:131], v[172:175], v[4:7], v[128:131]
	s_lshl_b32 s58, s65, 7
	s_add_u32 s56, s46, s56
	v_mfma_f32_16x16x32_bf16 v[132:135], v[180:183], v[4:7], v[132:135]
	s_addc_u32 s57, s47, 0
	s_add_u32 s58, s48, s58
	v_mfma_f32_16x16x32_bf16 v[136:139], v[188:191], v[4:7], v[136:139]
	s_addc_u32 s59, s49, 0
	global_load_dwordx4 v[104:107], v117, s[56:57]
	global_load_dwordx4 v[108:111], v118, s[58:59]
	s_cmp_eq_u32 s64, 0
	s_cbranch_scc1 .Lnsa_nm_11
	v_lshl_add_u32 v222, v113, 2, s44
	v_sub_u32_e32 v120, v86, v222
	v_cndmask_b32_e64 v240, -1, v120, s[60:61]
	v_subrev_u32_e32 v220, 0, v240
	v_subrev_u32_e32 v221, 1, v240
	v_subrev_u32_e32 v222, 2, v240
	v_subrev_u32_e32 v223, 3, v240
	v_cmp_gt_u32_e64 s[52:53], s45, v220
	v_cmp_gt_u32_e64 s[54:55], s45, v221
	v_cmp_gt_u32_e64 s[56:57], s45, v222
	v_cmp_gt_u32_e64 s[58:59], s45, v223
	v_cndmask_b32_e64 v124, v224, v124, s[52:53]
	v_cndmask_b32_e64 v125, v224, v125, s[54:55]
	v_cndmask_b32_e64 v126, v224, v126, s[56:57]
	v_cndmask_b32_e64 v127, v224, v127, s[58:59]
	v_subrev_u32_e32 v220, 16, v240
	v_subrev_u32_e32 v221, 17, v240
	v_subrev_u32_e32 v222, 18, v240
	v_subrev_u32_e32 v223, 19, v240
	v_cmp_gt_u32_e64 s[52:53], s45, v220
	v_cmp_gt_u32_e64 s[54:55], s45, v221
	v_cmp_gt_u32_e64 s[56:57], s45, v222
	v_cmp_gt_u32_e64 s[58:59], s45, v223
	v_cndmask_b32_e64 v128, v224, v128, s[52:53]
	v_cndmask_b32_e64 v129, v224, v129, s[54:55]
	v_cndmask_b32_e64 v130, v224, v130, s[56:57]
	v_cndmask_b32_e64 v131, v224, v131, s[58:59]
	v_subrev_u32_e32 v220, 32, v240
	v_subrev_u32_e32 v221, 33, v240
	v_subrev_u32_e32 v222, 34, v240
	v_subrev_u32_e32 v223, 35, v240
	v_cmp_gt_u32_e64 s[52:53], s45, v220
	v_cmp_gt_u32_e64 s[54:55], s45, v221
	v_cmp_gt_u32_e64 s[56:57], s45, v222
	v_cmp_gt_u32_e64 s[58:59], s45, v223
	v_cndmask_b32_e64 v132, v224, v132, s[52:53]
	v_cndmask_b32_e64 v133, v224, v133, s[54:55]
	v_cndmask_b32_e64 v134, v224, v134, s[56:57]
	v_cndmask_b32_e64 v135, v224, v135, s[58:59]
	v_subrev_u32_e32 v220, 48, v240
	v_subrev_u32_e32 v221, 49, v240
	v_subrev_u32_e32 v222, 50, v240
	v_subrev_u32_e32 v223, 51, v240
	v_cmp_gt_u32_e64 s[52:53], s45, v220
	v_cmp_gt_u32_e64 s[54:55], s45, v221
	v_cmp_gt_u32_e64 s[56:57], s45, v222
	v_cmp_gt_u32_e64 s[58:59], s45, v223
	v_cndmask_b32_e64 v136, v224, v136, s[52:53]
	v_cndmask_b32_e64 v137, v224, v137, s[54:55]
	v_cndmask_b32_e64 v138, v224, v138, s[56:57]
	v_cndmask_b32_e64 v139, v224, v139, s[58:59]

.Lnsa_rb_15:
	s_waitcnt lgkmcnt(0)
	s_barrier
	s_mov_b32 s50, s17
	s_mov_b32 s15, s16
	v_add_u32_e32 v225, s50, v115
	v_add_u32_e32 v246, s50, v122
	ds_read_b128 v[160:163], v225 offset:0
	ds_read_b128 v[168:171], v225 offset:2048
	ds_read_b128 v[176:179], v225 offset:4096
	ds_read_b128 v[184:187], v225 offset:6144
	ds_read_b128 v[164:167], v246 offset:0
	ds_read_b128 v[172:175], v246 offset:2048
	ds_read_b128 v[180:183], v246 offset:4096
	ds_read_b128 v[188:191], v246 offset:6144
	v_mfma_f32_16x16x32_bf16 v[48:51], v[16:19], v[204:207], v[48:51]
	v_exp_f32_e32 v140, v140
	v_exp_f32_e32 v141, v141
	v_exp_f32_e32 v142, v142
	v_exp_f32_e32 v143, v143
	v_mfma_f32_16x16x32_bf16 v[52:55], v[24:27], v[204:207], v[52:55]
	v_exp_f32_e32 v144, v144
	v_exp_f32_e32 v145, v145
	v_exp_f32_e32 v146, v146
	v_exp_f32_e32 v147, v147
	v_mfma_f32_16x16x32_bf16 v[56:59], v[32:35], v[204:207], v[56:59]
	v_exp_f32_e32 v148, v148
	v_exp_f32_e32 v149, v149
	v_exp_f32_e32 v150, v150
	v_exp_f32_e32 v151, v151
	v_mfma_f32_16x16x32_bf16 v[60:63], v[40:43], v[204:207], v[60:63]
	v_exp_f32_e32 v154, v154
	v_exp_f32_e32 v155, v155
	v_exp_f32_e32 v156, v156
	v_exp_f32_e32 v157, v157
	v_mfma_f32_16x16x32_bf16 v[48:51], v[20:23], v[208:211], v[48:51]
	v_add_f32_e32 v232, v140, v141
	v_add_f32_e32 v232, v232, v142
	v_add_f32_e32 v232, v232, v143
	v_add_f32_e32 v232, v232, v144
	v_mfma_f32_16x16x32_bf16 v[52:55], v[28:31], v[208:211], v[52:55]
	v_add_f32_e32 v232, v232, v145
	v_add_f32_e32 v232, v232, v146
	v_add_f32_e32 v232, v232, v147
	v_add_f32_e32 v232, v232, v148
	v_mfma_f32_16x16x32_bf16 v[56:59], v[36:39], v[208:211], v[56:59]
	v_add_f32_e32 v232, v232, v149
	v_add_f32_e32 v232, v232, v150
	v_add_f32_e32 v232, v232, v151
	v_add_f32_e32 v232, v232, v154
	v_mfma_f32_16x16x32_bf16 v[60:63], v[44:47], v[208:211], v[60:63]
	v_add_f32_e32 v232, v232, v155
	v_add_f32_e32 v232, v232, v156
	v_add_f32_e32 v232, v232, v157
	v_add_f32_e32 v83, v83, v232
	v_cvt_pk_bf16_f32 v212, v140, v141
	v_cvt_pk_bf16_f32 v213, v142, v143
	v_cvt_pk_bf16_f32 v214, v144, v145
	v_cvt_pk_bf16_f32 v215, v146, v147
	v_cvt_pk_bf16_f32 v216, v148, v149
	v_cvt_pk_bf16_f32 v217, v150, v151
	v_cvt_pk_bf16_f32 v218, v154, v155
	v_cvt_pk_bf16_f32 v219, v156, v157
	s_cmp_lt_i32 s15, 0
	s_cbranch_scc1 .Lnsa_brk_4
	s_waitcnt lgkmcnt(0)
	v_mfma_f32_16x16x32_bf16 v[64:67], v[16:19], v[212:215], v[64:67]
	s_lshl_b32 s44, s15, 6
	s_lshl_b32 s65, 1, s15
	v_and_b32_e32 v220, s65, v248
	v_mfma_f32_16x16x32_bf16 v[68:71], v[24:27], v[212:215], v[68:71]
	v_and_b32_e32 v221, s65, v249
	v_cmp_ne_u32_e64 s[60:61], 0, v220
	v_cmp_ne_u32_e64 s[62:63], 0, v221
	v_mfma_f32_16x16x32_bf16 v[72:75], v[32:35], v[212:215], v[72:75]
	s_cmp_eq_u32 s15, s32
	s_cselect_b32 s64, 1, 0
	s_cmp_eq_u32 s15, s14
	v_mfma_f32_16x16x32_bf16 v[76:79], v[40:43], v[212:215], v[76:79]
	s_cselect_b32 s64, 1, s64
	s_xor_b32 s17, s50, 0x4800
	v_add_u32_e32 v244, s17, v114
	v_mfma_f32_16x16x32_bf16 v[64:67], v[20:23], v[216:219], v[64:67]
	v_add_u32_e32 v245, s17, v123
	v_add_u32_e32 v247, s50, v116
	v_xor_b32_e32 v241, 16, v245
	v_mfma_f32_16x16x32_bf16 v[68:71], v[28:31], v[216:219], v[68:71]
	v_xor_b32_e32 v246, 64, v247
	v_cndmask_b32_e64 v228, v227, v80, s[60:61]
	v_cndmask_b32_e64 v229, v227, v80, s[60:61]
	v_mfma_f32_16x16x32_bf16 v[72:75], v[36:39], v[216:219], v[72:75]
	v_cndmask_b32_e64 v230, v227, v80, s[60:61]
	v_cndmask_b32_e64 v231, v227, v80, s[60:61]
	v_cndmask_b32_e64 v236, v227, v81, s[62:63]
	v_mfma_f32_16x16x32_bf16 v[76:79], v[44:47], v[216:219], v[76:79]
	v_cndmask_b32_e64 v237, v227, v81, s[62:63]
	v_cndmask_b32_e64 v238, v227, v81, s[62:63]
	v_cndmask_b32_e64 v239, v227, v81, s[62:63]
	ds_read_b128 v[16:19], v247 offset:0
	ds_read_b128 v[20:23], v246 offset:0
	ds_read_b128 v[24:27], v247 offset:2048
	ds_read_b128 v[28:31], v246 offset:2048
	ds_read_b128 v[32:35], v247 offset:4096
	ds_read_b128 v[36:39], v246 offset:4096
	ds_read_b128 v[40:43], v247 offset:6144
	ds_read_b128 v[44:47], v246 offset:6144
	v_mfma_f32_16x16x32_bf16 v[124:127], v[160:163], v[0:3], v[228:231]
	s_waitcnt vmcnt(4)
	ds_write_b128 v244, v[88:91]
	v_mfma_f32_16x16x32_bf16 v[128:131], v[168:171], v[0:3], v[228:231]
	ds_write_b64 v245, v[92:93]
	ds_write_b64 v241, v[94:95]
	v_mfma_f32_16x16x32_bf16 v[132:135], v[176:179], v[0:3], v[228:231]
	s_mov_b32 s16, s40
	s_ff1_i32_b32 s40, s38
	v_mfma_f32_16x16x32_bf16 v[136:139], v[184:187], v[0:3], v[228:231]
	s_add_i32 s65, s38, -1
	s_and_b32 s38, s38, s65
	v_mfma_f32_16x16x32_bf16 v[124:127], v[164:167], v[4:7], v[124:127]
	s_max_i32 s65, s40, 0
	s_mul_i32 s56, s65, 0x18000
	v_mfma_f32_16x16x32_bf16 v[128:131], v[172:175], v[4:7], v[128:131]
	s_lshl_b32 s58, s65, 7
	s_add_u32 s56, s46, s56
	v_mfma_f32_16x16x32_bf16 v[132:135], v[180:183], v[4:7], v[132:135]
	s_addc_u32 s57, s47, 0
	s_add_u32 s58, s48, s58
	v_mfma_f32_16x16x32_bf16 v[136:139], v[188:191], v[4:7], v[136:139]
	s_addc_u32 s59, s49, 0
	global_load_dwordx4 v[88:91], v117, s[56:57]
	global_load_dwordx4 v[92:95], v118, s[58:59]
	s_cmp_eq_u32 s64, 0
	s_cbranch_scc1 .Lnsa_nm_17
	v_lshl_add_u32 v222, v113, 2, s44
	v_sub_u32_e32 v120, v86, v222
	v_cndmask_b32_e64 v240, -1, v120, s[60:61]
	v_subrev_u32_e32 v220, 0, v240
	v_subrev_u32_e32 v221, 1, v240
	v_subrev_u32_e32 v222, 2, v240
	v_subrev_u32_e32 v223, 3, v240
	v_cmp_gt_u32_e64 s[52:53], s45, v220
	v_cmp_gt_u32_e64 s[54:55], s45, v221
	v_cmp_gt_u32_e64 s[56:57], s45, v222
	v_cmp_gt_u32_e64 s[58:59], s45, v223
	v_cndmask_b32_e64 v124, v224, v124, s[52:53]
	v_cndmask_b32_e64 v125, v224, v125, s[54:55]
	v_cndmask_b32_e64 v126, v224, v126, s[56:57]
	v_cndmask_b32_e64 v127, v224, v127, s[58:59]
	v_subrev_u32_e32 v220, 16, v240
	v_subrev_u32_e32 v221, 17, v240
	v_subrev_u32_e32 v222, 18, v240
	v_subrev_u32_e32 v223, 19, v240
	v_cmp_gt_u32_e64 s[52:53], s45, v220
	v_cmp_gt_u32_e64 s[54:55], s45, v221
	v_cmp_gt_u32_e64 s[56:57], s45, v222
	v_cmp_gt_u32_e64 s[58:59], s45, v223
	v_cndmask_b32_e64 v128, v224, v128, s[52:53]
	v_cndmask_b32_e64 v129, v224, v129, s[54:55]
	v_cndmask_b32_e64 v130, v224, v130, s[56:57]
	v_cndmask_b32_e64 v131, v224, v131, s[58:59]
	v_subrev_u32_e32 v220, 32, v240
	v_subrev_u32_e32 v221, 33, v240
	v_subrev_u32_e32 v222, 34, v240
	v_subrev_u32_e32 v223, 35, v240
	v_cmp_gt_u32_e64 s[52:53], s45, v220
	v_cmp_gt_u32_e64 s[54:55], s45, v221
	v_cmp_gt_u32_e64 s[56:57], s45, v222
	v_cmp_gt_u32_e64 s[58:59], s45, v223
	v_cndmask_b32_e64 v132, v224, v132, s[52:53]
	v_cndmask_b32_e64 v133, v224, v133, s[54:55]
	v_cndmask_b32_e64 v134, v224, v134, s[56:57]
	v_cndmask_b32_e64 v135, v224, v135, s[58:59]
	v_subrev_u32_e32 v220, 48, v240
	v_subrev_u32_e32 v221, 49, v240
	v_subrev_u32_e32 v222, 50, v240
	v_subrev_u32_e32 v223, 51, v240
	v_cmp_gt_u32_e64 s[52:53], s45, v220
	v_cmp_gt_u32_e64 s[54:55], s45, v221
	v_cmp_gt_u32_e64 s[56:57], s45, v222
	v_cmp_gt_u32_e64 s[58:59], s45, v223
	v_cndmask_b32_e64 v136, v224, v136, s[52:53]
	v_cndmask_b32_e64 v137, v224, v137, s[54:55]
	v_cndmask_b32_e64 v138, v224, v138, s[56:57]
	v_cndmask_b32_e64 v139, v224, v139, s[58:59]
